# prologue W_in transpose item: 32 weight + 32 gain loads issued before the first wait (was one load per vmcnt(0)); stacked on tables-in-idle-tail, hand-written attention phase, P2 staging
# speedup vs baseline: 1.0372x; 1.0201x over previous
; #define LAS __attribute__((address_space(3)))
; __device__ __forceinline__ void p0_transpose_item(const float* W, int K, int N, bf16* WT, const float* ks, int radd, LAS float* scr, int kb, int nb, int lane) {
;     const int k0 = 64 * kb, n0 = 32 * nb;
; #pragma unroll 8
;     for (int i = 0; i < 32; ++i) { const int kk = 2 * i + (lane >> 5); const float s = ks ? ks[k0 + kk] : 1.0f; scr[kk * 33 + (lane & 31)] = __builtin_nontemporal_load(W + (size_t)(k0 + kk) * N + n0 + (lane & 31)) * s; }
; __device__ __forceinline__ void p0_prologue(const Ptrs& P, LAS unsigned char* lds, int gw, int NGW, int wave, int lane, int gtid, int GT, int part) {
;     ...
;         if (r < I0) { const int nblk = NIN0 / 32; p0_transpose_item(P.lwin, D, NIN0, W0T, P.norm_g, 0, scr, r / nblk, r % nblk, lane); continue; } r -= I0;
.LBB0_26:
	s_andn2_b64 vcc, exec, s[2:3]
	s_cbranch_vccnz .LBB0_9
	s_mul_hi_i32 s2, s74, 0x66666667
	s_lshr_b32 s3, s2, 31
	s_ashr_i32 s2, s2, 5
	s_add_i32 s2, s2, s3
	s_mul_i32 s3, s2, 0x50
	s_sub_i32 s3, s74, s3
	s_lshl_b32 s28, s2, 6
	s_lshl_b32 s26, s3, 5
	s_ashr_i32 s29, s28, 31
	s_ashr_i32 s27, s26, 31
	v_mov_b32_e32 v25, s29
	v_or_b32_e32 v24, s28, v2
	v_lshl_add_u64 v[22:23], s[26:27], 2, v[14:15]
	v_lshl_add_u64 v[26:27], v[24:25], 2, s[24:25]
	v_mul_u32_u24_e32 v164, 0x2800, v2
	v_and_b32_e32 v165, 31, v232
	v_lshl_add_u32 v164, v165, 2, v164
	v_lshlrev_b32_e32 v165, 2, v2
	s_mul_i32 s100, s28, 0x2800
	s_lshl_b32 s96, s26, 2
	s_add_u32 s96, s96, s100
	s_add_u32 s96, s42, s96
	s_addc_u32 s97, s43, 0
	s_lshl_b32 s100, s28, 2
	s_add_u32 s98, s38, s100
	s_addc_u32 s99, s39, 0
	global_load_dword v132, v165, s[98:99]
	global_load_dword v133, v165, s[98:99] offset:8
	global_load_dword v134, v165, s[98:99] offset:16
	global_load_dword v135, v165, s[98:99] offset:24
	global_load_dword v136, v165, s[98:99] offset:32
	global_load_dword v137, v165, s[98:99] offset:40
	global_load_dword v138, v165, s[98:99] offset:48
	global_load_dword v139, v165, s[98:99] offset:56
	global_load_dword v140, v165, s[98:99] offset:64
	global_load_dword v141, v165, s[98:99] offset:72
	global_load_dword v142, v165, s[98:99] offset:80
	global_load_dword v143, v165, s[98:99] offset:88
	global_load_dword v144, v165, s[98:99] offset:96
	global_load_dword v145, v165, s[98:99] offset:104
	global_load_dword v146, v165, s[98:99] offset:112
	global_load_dword v147, v165, s[98:99] offset:120
	global_load_dword v148, v165, s[98:99] offset:128
	global_load_dword v149, v165, s[98:99] offset:136
	global_load_dword v150, v165, s[98:99] offset:144
	global_load_dword v151, v165, s[98:99] offset:152
	global_load_dword v152, v165, s[98:99] offset:160
	global_load_dword v153, v165, s[98:99] offset:168
	global_load_dword v154, v165, s[98:99] offset:176
	global_load_dword v155, v165, s[98:99] offset:184
	global_load_dword v156, v165, s[98:99] offset:192
	global_load_dword v157, v165, s[98:99] offset:200
	global_load_dword v158, v165, s[98:99] offset:208
	global_load_dword v159, v165, s[98:99] offset:216
	global_load_dword v160, v165, s[98:99] offset:224
	global_load_dword v161, v165, s[98:99] offset:232
	global_load_dword v162, v165, s[98:99] offset:240
	global_load_dword v163, v165, s[98:99] offset:248
	global_load_dword v100, v164, s[96:97] nt
	s_add_u32 s96, s96, 0x5000
	s_addc_u32 s97, s97, 0
	global_load_dword v101, v164, s[96:97] nt
	s_add_u32 s96, s96, 0x5000
	s_addc_u32 s97, s97, 0
	global_load_dword v102, v164, s[96:97] nt
	s_add_u32 s96, s96, 0x5000
	s_addc_u32 s97, s97, 0
	global_load_dword v103, v164, s[96:97] nt
	s_add_u32 s96, s96, 0x5000
	s_addc_u32 s97, s97, 0
	global_load_dword v104, v164, s[96:97] nt
	s_add_u32 s96, s96, 0x5000
	s_addc_u32 s97, s97, 0
	global_load_dword v105, v164, s[96:97] nt
	s_add_u32 s96, s96, 0x5000
	s_addc_u32 s97, s97, 0
	global_load_dword v106, v164, s[96:97] nt
	s_add_u32 s96, s96, 0x5000
	s_addc_u32 s97, s97, 0
	global_load_dword v107, v164, s[96:97] nt
	s_add_u32 s96, s96, 0x5000
	s_addc_u32 s97, s97, 0
	global_load_dword v108, v164, s[96:97] nt
	s_add_u32 s96, s96, 0x5000
	s_addc_u32 s97, s97, 0
	global_load_dword v109, v164, s[96:97] nt
	s_add_u32 s96, s96, 0x5000
	s_addc_u32 s97, s97, 0
	global_load_dword v110, v164, s[96:97] nt
	s_add_u32 s96, s96, 0x5000
	s_addc_u32 s97, s97, 0
	global_load_dword v111, v164, s[96:97] nt
	s_add_u32 s96, s96, 0x5000
	s_addc_u32 s97, s97, 0
	global_load_dword v112, v164, s[96:97] nt
	s_add_u32 s96, s96, 0x5000
	s_addc_u32 s97, s97, 0
	global_load_dword v113, v164, s[96:97] nt
	s_add_u32 s96, s96, 0x5000
	s_addc_u32 s97, s97, 0
	global_load_dword v114, v164, s[96:97] nt
	s_add_u32 s96, s96, 0x5000
	s_addc_u32 s97, s97, 0
	global_load_dword v115, v164, s[96:97] nt
	s_add_u32 s96, s96, 0x5000
	s_addc_u32 s97, s97, 0
	global_load_dword v116, v164, s[96:97] nt
	s_add_u32 s96, s96, 0x5000
	s_addc_u32 s97, s97, 0
	global_load_dword v117, v164, s[96:97] nt
	s_add_u32 s96, s96, 0x5000
	s_addc_u32 s97, s97, 0
	global_load_dword v118, v164, s[96:97] nt
	s_add_u32 s96, s96, 0x5000
	s_addc_u32 s97, s97, 0
	global_load_dword v119, v164, s[96:97] nt
	s_add_u32 s96, s96, 0x5000
	s_addc_u32 s97, s97, 0
	global_load_dword v120, v164, s[96:97] nt
	s_add_u32 s96, s96, 0x5000
	s_addc_u32 s97, s97, 0
	global_load_dword v121, v164, s[96:97] nt
	s_add_u32 s96, s96, 0x5000
	s_addc_u32 s97, s97, 0
	global_load_dword v122, v164, s[96:97] nt
	s_add_u32 s96, s96, 0x5000
	s_addc_u32 s97, s97, 0
	global_load_dword v123, v164, s[96:97] nt
	s_add_u32 s96, s96, 0x5000
	s_addc_u32 s97, s97, 0
	global_load_dword v124, v164, s[96:97] nt
	s_add_u32 s96, s96, 0x5000
	s_addc_u32 s97, s97, 0
	global_load_dword v125, v164, s[96:97] nt
	s_add_u32 s96, s96, 0x5000
	s_addc_u32 s97, s97, 0
	global_load_dword v126, v164, s[96:97] nt
	s_add_u32 s96, s96, 0x5000
	s_addc_u32 s97, s97, 0
	global_load_dword v127, v164, s[96:97] nt
	s_add_u32 s96, s96, 0x5000
	s_addc_u32 s97, s97, 0
	global_load_dword v128, v164, s[96:97] nt
	s_add_u32 s96, s96, 0x5000
	s_addc_u32 s97, s97, 0
	global_load_dword v129, v164, s[96:97] nt
	s_add_u32 s96, s96, 0x5000
	s_addc_u32 s97, s97, 0
	global_load_dword v130, v164, s[96:97] nt
	s_add_u32 s96, s96, 0x5000
	s_addc_u32 s97, s97, 0
	global_load_dword v131, v164, s[96:97] nt
	s_waitcnt vmcnt(31)
; #define LDS_WAIT() asm volatile("s_waitcnt lgkmcnt(0)" ::: "memory")
; __device__ __forceinline__ void p0_transpose_item(const float* W, int K, int N, bf16* WT, const float* ks, int radd, LAS float* scr, int kb, int nb, int lane) {
;     ...
;     for (int i = 0; i < 32; ++i) { const int kk = 2 * i + (lane >> 5); const float s = ks ? ks[k0 + kk] : 1.0f; scr[kk * 33 + (lane & 31)] = __builtin_nontemporal_load(W + (size_t)(k0 + kk) * N + n0 + (lane & 31)) * s; }
;     LDS_WAIT(); asm volatile("" ::: "memory");
	v_mul_f32_e32 v100, v132, v100
	ds_write_b32 v57, v100
	s_waitcnt vmcnt(30)
	v_mul_f32_e32 v101, v133, v101
	ds_write_b32 v57, v101 offset:264
	s_waitcnt vmcnt(29)
	v_mul_f32_e32 v102, v134, v102
	ds_write_b32 v57, v102 offset:528
	s_waitcnt vmcnt(28)
	v_mul_f32_e32 v103, v135, v103
	ds_write_b32 v57, v103 offset:792
	s_waitcnt vmcnt(27)
	v_mul_f32_e32 v104, v136, v104
	ds_write_b32 v57, v104 offset:1056
	s_waitcnt vmcnt(26)
	v_mul_f32_e32 v105, v137, v105
	ds_write_b32 v57, v105 offset:1320
	s_waitcnt vmcnt(25)
	v_mul_f32_e32 v106, v138, v106
	ds_write_b32 v57, v106 offset:1584
	s_waitcnt vmcnt(24)
	v_mul_f32_e32 v107, v139, v107
	ds_write_b32 v57, v107 offset:1848
	s_waitcnt vmcnt(23)
	v_mul_f32_e32 v108, v140, v108
	ds_write_b32 v57, v108 offset:2112
	s_waitcnt vmcnt(22)
	v_mul_f32_e32 v109, v141, v109
	ds_write_b32 v57, v109 offset:2376
	s_waitcnt vmcnt(21)
	v_mul_f32_e32 v110, v142, v110
	ds_write_b32 v57, v110 offset:2640
	s_waitcnt vmcnt(20)
	v_mul_f32_e32 v111, v143, v111
	ds_write_b32 v57, v111 offset:2904
	s_waitcnt vmcnt(19)
	v_mul_f32_e32 v112, v144, v112
	ds_write_b32 v57, v112 offset:3168
	s_waitcnt vmcnt(18)
	v_mul_f32_e32 v113, v145, v113
	ds_write_b32 v57, v113 offset:3432
	s_waitcnt vmcnt(17)
	v_mul_f32_e32 v114, v146, v114
	ds_write_b32 v57, v114 offset:3696
	s_waitcnt vmcnt(16)
	v_mul_f32_e32 v115, v147, v115
	ds_write_b32 v57, v115 offset:3960
	s_waitcnt vmcnt(15)
	v_mul_f32_e32 v116, v148, v116
	ds_write_b32 v57, v116 offset:4224
	s_waitcnt vmcnt(14)
	v_mul_f32_e32 v117, v149, v117
	ds_write_b32 v57, v117 offset:4488
	s_waitcnt vmcnt(13)
	v_mul_f32_e32 v118, v150, v118
	ds_write_b32 v57, v118 offset:4752
	s_waitcnt vmcnt(12)
	v_mul_f32_e32 v119, v151, v119
	ds_write_b32 v57, v119 offset:5016
	s_waitcnt vmcnt(11)
	v_mul_f32_e32 v120, v152, v120
	ds_write_b32 v57, v120 offset:5280
	s_waitcnt vmcnt(10)
	v_mul_f32_e32 v121, v153, v121
	ds_write_b32 v57, v121 offset:5544
	s_waitcnt vmcnt(9)
	v_mul_f32_e32 v122, v154, v122
	ds_write_b32 v57, v122 offset:5808
	s_waitcnt vmcnt(8)
	v_mul_f32_e32 v123, v155, v123
	ds_write_b32 v57, v123 offset:6072
	s_waitcnt vmcnt(7)
	v_mul_f32_e32 v124, v156, v124
	ds_write_b32 v57, v124 offset:6336
	s_waitcnt vmcnt(6)
	v_mul_f32_e32 v125, v157, v125
	ds_write_b32 v57, v125 offset:6600
	s_waitcnt vmcnt(5)
	v_mul_f32_e32 v126, v158, v126
	ds_write_b32 v57, v126 offset:6864
	s_waitcnt vmcnt(4)
	v_mul_f32_e32 v127, v159, v127
	ds_write_b32 v57, v127 offset:7128
	s_waitcnt vmcnt(3)
	v_mul_f32_e32 v128, v160, v128
	ds_write_b32 v57, v128 offset:7392
	s_waitcnt vmcnt(2)
	v_mul_f32_e32 v129, v161, v129
	ds_write_b32 v57, v129 offset:7656
	s_waitcnt vmcnt(1)
	v_mul_f32_e32 v130, v162, v130
	ds_write_b32 v57, v130 offset:7920
	s_waitcnt vmcnt(0)
	v_mul_f32_e32 v131, v163, v131
	ds_write_b32 v57, v131 offset:8184
	s_branch .LBB0_8
